# cand G + P7 unit transition: rstd-table wait counted (vmcnt(16): the 4 partial-sum loads are older than the 16 H stores) instead of vmcnt(0)
# baseline (speedup 1.0000x reference)
.LBB0_1228:
	s_or_b64 exec, exec, s[30:31]
	v_lshl_add_u32 v165, s65, 10, v162
	ds_read2_b32 v[168:169], v165 offset1:16
	v_lshl_add_u32 v166, s26, 8, v159
	v_lshl_add_u32 v156, s27, 8, v161
	v_ashrrev_i32_e32 v167, 31, v166
	v_ashrrev_i32_e32 v157, 31, v156
	s_waitcnt lgkmcnt(0)
	v_pk_mul_f32 v[138:139], v[138:139], v[168:169] op_sel_hi:[1,0]
	v_pk_mul_f32 v[142:143], v[142:143], v[168:169] op_sel_hi:[1,0]
	v_pk_mul_f32 v[140:141], v[140:141], v[168:169] op_sel_hi:[1,0]
	v_max_f32_e32 v138, 0, v138
	v_lshlrev_b64 v[170:171], 13, v[166:167]
	v_pk_mul_f32 v[144:145], v[144:145], v[168:169] op_sel_hi:[1,0]
	v_mul_f32_e32 v167, v138, v138
	v_max_f32_e32 v138, 0, v143
	v_max_f32_e32 v139, 0, v139
	v_max_f32_e32 v140, 0, v140
	v_lshl_add_u64 v[170:171], s[14:15], 0, v[170:171]
	v_lshlrev_b64 v[172:173], 1, v[156:157]
	v_max_f32_e32 v142, 0, v142
	v_mul_f32_e32 v138, v138, v138
	v_mul_f32_e32 v143, v139, v139
	v_max_f32_e32 v139, 0, v144
	v_mul_f32_e32 v144, v140, v140
	v_max_f32_e32 v140, 0, v145
	v_max_f32_e32 v141, 0, v141
	v_pk_mul_f32 v[132:133], v[132:133], v[168:169] op_sel_hi:[1,0]
	v_pk_mul_f32 v[130:131], v[130:131], v[168:169] op_sel_hi:[1,0]
	v_lshl_add_u64 v[156:157], v[170:171], 0, v[172:173]
	v_mul_f32_e32 v142, v142, v142
	v_mul_f32_e32 v139, v139, v139
	v_mul_f32_e32 v140, v140, v140
	v_mul_f32_e32 v141, v141, v141
	v_cvt_pk_bf16_f32 v138, v142, v138
	v_pk_mul_f32 v[136:137], v[136:137], v[168:169] op_sel_hi:[1,0]
	v_pk_mul_f32 v[134:135], v[134:135], v[168:169] op_sel_hi:[1,0]
	v_max_f32_e32 v130, 0, v130
	v_max_f32_e32 v131, 0, v131
	v_max_f32_e32 v132, 0, v132
	v_cvt_pk_bf16_f32 v139, v139, v140
	v_cvt_pk_bf16_f32 v140, v167, v143
	v_cvt_pk_bf16_f32 v141, v144, v141
	global_store_dwordx4 v[156:157], v[138:141], off sc1
	v_max_f32_e32 v133, 0, v133
	v_max_f32_e32 v134, 0, v134
	v_mul_f32_e32 v138, v130, v130
	v_max_f32_e32 v130, 0, v135
	v_mul_f32_e32 v135, v131, v131
	v_max_f32_e32 v131, 0, v136
	v_mul_f32_e32 v136, v132, v132
	v_max_f32_e32 v132, 0, v137
	v_mul_f32_e32 v131, v131, v131
	v_mul_f32_e32 v132, v132, v132
	v_mul_f32_e32 v130, v130, v130
	v_mul_f32_e32 v133, v133, v133
	v_cvt_pk_bf16_f32 v131, v131, v132
	v_cvt_pk_bf16_f32 v132, v138, v135
	v_mul_f32_e32 v134, v134, v134
	v_cvt_pk_bf16_f32 v130, v134, v130
	v_cvt_pk_bf16_f32 v133, v136, v133
	global_store_dwordx4 v[156:157], v[130:133], off offset:256 sc1
	s_mov_b32 s19, 0x100000
	s_mov_b64 s[26:27], 0x100000
	v_mov_b32_e32 v132, v169
	v_or_b32_e32 v130, 16, v166
	v_pk_mul_f32 v[122:123], v[122:123], v[132:133] op_sel_hi:[1,0]
	v_ashrrev_i32_e32 v131, 31, v130
	v_pk_mul_f32 v[126:127], v[126:127], v[132:133] op_sel_hi:[1,0]
	v_pk_mul_f32 v[124:125], v[124:125], v[132:133] op_sel_hi:[1,0]
	v_max_f32_e32 v122, 0, v122
	v_lshlrev_b64 v[130:131], 13, v[130:131]
	v_pk_mul_f32 v[128:129], v[128:129], v[132:133] op_sel_hi:[1,0]
	v_mul_f32_e32 v133, v122, v122
	v_max_f32_e32 v122, 0, v127
	v_max_f32_e32 v123, 0, v123
	v_max_f32_e32 v124, 0, v124
	v_lshl_add_u64 v[130:131], s[14:15], 0, v[130:131]
	v_max_f32_e32 v126, 0, v126
	v_mul_f32_e32 v122, v122, v122
	v_mul_f32_e32 v127, v123, v123
	v_max_f32_e32 v123, 0, v128
	v_mul_f32_e32 v128, v124, v124
	v_max_f32_e32 v124, 0, v129
	v_max_f32_e32 v125, 0, v125
	v_pk_mul_f32 v[116:117], v[116:117], v[132:133] op_sel_hi:[1,0]
	v_pk_mul_f32 v[114:115], v[114:115], v[132:133] op_sel_hi:[1,0]
	v_lshl_add_u64 v[130:131], v[130:131], 0, v[172:173]
	v_mul_f32_e32 v126, v126, v126
	v_mul_f32_e32 v123, v123, v123
	v_mul_f32_e32 v124, v124, v124
	v_mul_f32_e32 v125, v125, v125
	v_cvt_pk_bf16_f32 v122, v126, v122
	v_pk_mul_f32 v[120:121], v[120:121], v[132:133] op_sel_hi:[1,0]
	v_pk_mul_f32 v[118:119], v[118:119], v[132:133] op_sel_hi:[1,0]
	v_max_f32_e32 v114, 0, v114
	v_max_f32_e32 v115, 0, v115
	v_max_f32_e32 v116, 0, v116
	v_cvt_pk_bf16_f32 v123, v123, v124
	v_cvt_pk_bf16_f32 v124, v133, v127
	v_cvt_pk_bf16_f32 v125, v128, v125
	global_store_dwordx4 v[130:131], v[122:125], off sc1
	v_max_f32_e32 v117, 0, v117
	v_mul_f32_e32 v117, v117, v117
	v_mul_f32_e32 v122, v114, v114
	v_max_f32_e32 v114, 0, v119
	v_mul_f32_e32 v119, v115, v115
	v_max_f32_e32 v115, 0, v120
	v_mul_f32_e32 v120, v116, v116
	v_max_f32_e32 v116, 0, v121
	v_mul_f32_e32 v115, v115, v115
	v_mul_f32_e32 v116, v116, v116
	v_max_f32_e32 v118, 0, v118
	v_mul_f32_e32 v114, v114, v114
	v_cvt_pk_bf16_f32 v115, v115, v116
	v_cvt_pk_bf16_f32 v116, v122, v119
	v_cvt_pk_bf16_f32 v117, v120, v117
	v_mul_f32_e32 v118, v118, v118
	v_cvt_pk_bf16_f32 v114, v118, v114
	global_store_dwordx4 v[130:131], v[114:117], off offset:256 sc1
	ds_read2_b32 v[116:117], v165 offset0:32 offset1:48
	s_waitcnt lgkmcnt(0)
	v_pk_mul_f32 v[106:107], v[106:107], v[116:117] op_sel_hi:[1,0]
	v_or_b32_e32 v114, 32, v166
	v_ashrrev_i32_e32 v115, 31, v114
	v_pk_mul_f32 v[110:111], v[110:111], v[116:117] op_sel_hi:[1,0]
	v_pk_mul_f32 v[108:109], v[108:109], v[116:117] op_sel_hi:[1,0]
	v_max_f32_e32 v106, 0, v106
	v_lshlrev_b64 v[114:115], 13, v[114:115]
	v_pk_mul_f32 v[112:113], v[112:113], v[116:117] op_sel_hi:[1,0]
	v_mul_f32_e32 v118, v106, v106
	v_max_f32_e32 v106, 0, v111
	v_max_f32_e32 v107, 0, v107
	v_max_f32_e32 v108, 0, v108
	v_lshl_add_u64 v[114:115], s[14:15], 0, v[114:115]
	v_max_f32_e32 v110, 0, v110
	v_mul_f32_e32 v106, v106, v106
	v_mul_f32_e32 v111, v107, v107
	v_max_f32_e32 v107, 0, v112
	v_mul_f32_e32 v112, v108, v108
	v_max_f32_e32 v108, 0, v113
	v_max_f32_e32 v109, 0, v109
	v_pk_mul_f32 v[100:101], v[100:101], v[116:117] op_sel_hi:[1,0]
	v_pk_mul_f32 v[98:99], v[98:99], v[116:117] op_sel_hi:[1,0]
	v_lshl_add_u64 v[114:115], v[114:115], 0, v[172:173]
	v_mul_f32_e32 v110, v110, v110
	v_mul_f32_e32 v107, v107, v107
	v_mul_f32_e32 v108, v108, v108
	v_mul_f32_e32 v109, v109, v109
	v_cvt_pk_bf16_f32 v106, v110, v106
	v_pk_mul_f32 v[104:105], v[104:105], v[116:117] op_sel_hi:[1,0]
	v_pk_mul_f32 v[102:103], v[102:103], v[116:117] op_sel_hi:[1,0]
	v_max_f32_e32 v98, 0, v98
	v_max_f32_e32 v99, 0, v99
	v_max_f32_e32 v100, 0, v100
	v_cvt_pk_bf16_f32 v107, v107, v108
	v_cvt_pk_bf16_f32 v108, v118, v111
	v_cvt_pk_bf16_f32 v109, v112, v109
	global_store_dwordx4 v[114:115], v[106:109], off sc1
	v_max_f32_e32 v101, 0, v101
	v_max_f32_e32 v102, 0, v102
	v_mul_f32_e32 v106, v98, v98
	v_max_f32_e32 v98, 0, v103
	v_mul_f32_e32 v103, v99, v99
	v_max_f32_e32 v99, 0, v104
	v_mul_f32_e32 v104, v100, v100
	v_max_f32_e32 v100, 0, v105
	v_mul_f32_e32 v99, v99, v99
	v_mul_f32_e32 v100, v100, v100
	v_mul_f32_e32 v98, v98, v98
	v_mul_f32_e32 v101, v101, v101
	v_cvt_pk_bf16_f32 v99, v99, v100
	v_cvt_pk_bf16_f32 v100, v106, v103
	v_mul_f32_e32 v102, v102, v102
	v_cvt_pk_bf16_f32 v98, v102, v98
	v_cvt_pk_bf16_f32 v101, v104, v101
	global_store_dwordx4 v[114:115], v[98:101], off offset:256 sc1
	s_nop 1
	v_mov_b32_e32 v100, v117
	v_or_b32_e32 v98, 48, v166
	v_pk_mul_f32 v[90:91], v[90:91], v[100:101] op_sel_hi:[1,0]
	v_ashrrev_i32_e32 v99, 31, v98
	v_pk_mul_f32 v[94:95], v[94:95], v[100:101] op_sel_hi:[1,0]
	v_pk_mul_f32 v[92:93], v[92:93], v[100:101] op_sel_hi:[1,0]
	v_max_f32_e32 v90, 0, v90
	v_lshlrev_b64 v[98:99], 13, v[98:99]
	v_pk_mul_f32 v[96:97], v[96:97], v[100:101] op_sel_hi:[1,0]
	v_mul_f32_e32 v101, v90, v90
	v_max_f32_e32 v90, 0, v95
	v_max_f32_e32 v91, 0, v91
	v_max_f32_e32 v92, 0, v92
	v_lshl_add_u64 v[98:99], s[14:15], 0, v[98:99]
	v_max_f32_e32 v94, 0, v94
	v_mul_f32_e32 v90, v90, v90
	v_mul_f32_e32 v95, v91, v91
	v_max_f32_e32 v91, 0, v96
	v_mul_f32_e32 v96, v92, v92
	v_max_f32_e32 v92, 0, v97
	v_max_f32_e32 v93, 0, v93
	v_pk_mul_f32 v[82:83], v[82:83], v[100:101] op_sel_hi:[1,0]
	v_lshl_add_u64 v[98:99], v[98:99], 0, v[172:173]
	v_mul_f32_e32 v94, v94, v94
	v_mul_f32_e32 v91, v91, v91
	v_mul_f32_e32 v92, v92, v92
	v_mul_f32_e32 v93, v93, v93
	v_cvt_pk_bf16_f32 v90, v94, v90
	v_pk_mul_f32 v[86:87], v[86:87], v[100:101] op_sel_hi:[1,0]
	v_max_f32_e32 v82, 0, v82
	v_cvt_pk_bf16_f32 v91, v91, v92
	v_cvt_pk_bf16_f32 v92, v101, v95
	v_cvt_pk_bf16_f32 v93, v96, v93
	global_store_dwordx4 v[98:99], v[90:93], off sc1
	v_max_f32_e32 v86, 0, v86
	v_mul_f32_e32 v86, v86, v86
	v_mul_f32_e32 v90, v82, v82
	v_max_f32_e32 v82, 0, v87
	v_mul_f32_e32 v82, v82, v82
	v_cvt_pk_bf16_f32 v82, v86, v82
	ds_read2_b32 v[86:87], v165 offset0:128 offset1:144
	v_pk_mul_f32 v[84:85], v[84:85], v[100:101] op_sel_hi:[1,0]
	v_pk_mul_f32 v[88:89], v[88:89], v[100:101] op_sel_hi:[1,0]
	v_max_f32_e32 v83, 0, v83
	v_max_f32_e32 v84, 0, v84
	v_mul_f32_e32 v91, v83, v83
	v_max_f32_e32 v83, 0, v88
	v_mul_f32_e32 v88, v84, v84
	v_max_f32_e32 v84, 0, v89
	v_mul_f32_e32 v83, v83, v83
	v_max_f32_e32 v85, 0, v85
	v_mul_f32_e32 v84, v84, v84
	s_waitcnt lgkmcnt(0)
	v_pk_mul_f32 v[74:75], v[74:75], v[86:87] op_sel_hi:[1,0]
	v_mul_f32_e32 v85, v85, v85
	v_cvt_pk_bf16_f32 v83, v83, v84
	v_cvt_pk_bf16_f32 v84, v90, v91
	v_pk_mul_f32 v[78:79], v[78:79], v[86:87] op_sel_hi:[1,0]
	v_pk_mul_f32 v[76:77], v[76:77], v[86:87] op_sel_hi:[1,0]
	v_max_f32_e32 v74, 0, v74
	v_cvt_pk_bf16_f32 v85, v88, v85
	global_store_dwordx4 v[98:99], v[82:85], off offset:256 sc1
	v_pk_mul_f32 v[80:81], v[80:81], v[86:87] op_sel_hi:[1,0]
	v_max_f32_e32 v78, 0, v78
	v_mul_f32_e32 v84, v74, v74
	v_max_f32_e32 v74, 0, v79
	v_max_f32_e32 v75, 0, v75
	v_max_f32_e32 v76, 0, v76
	v_mul_f32_e32 v78, v78, v78
	v_mul_f32_e32 v74, v74, v74
	v_mul_f32_e32 v79, v75, v75
	v_max_f32_e32 v75, 0, v80
	v_mul_f32_e32 v80, v76, v76
	v_max_f32_e32 v76, 0, v81
	v_mul_f32_e32 v75, v75, v75
	v_max_f32_e32 v77, 0, v77
	v_mul_f32_e32 v76, v76, v76
	v_cvt_pk_bf16_f32 v74, v78, v74
	v_add_co_u32_e32 v78, vcc, s19, v156
	v_pk_mul_f32 v[68:69], v[68:69], v[86:87] op_sel_hi:[1,0]
	v_pk_mul_f32 v[66:67], v[66:67], v[86:87] op_sel_hi:[1,0]
	v_mul_f32_e32 v77, v77, v77
	v_cvt_pk_bf16_f32 v75, v75, v76
	v_cvt_pk_bf16_f32 v76, v84, v79
	v_addc_co_u32_e32 v79, vcc, 0, v157, vcc
	v_pk_mul_f32 v[72:73], v[72:73], v[86:87] op_sel_hi:[1,0]
	v_pk_mul_f32 v[70:71], v[70:71], v[86:87] op_sel_hi:[1,0]
	v_max_f32_e32 v66, 0, v66
	v_max_f32_e32 v67, 0, v67
	v_max_f32_e32 v68, 0, v68
	v_cvt_pk_bf16_f32 v77, v80, v77
	global_store_dwordx4 v[78:79], v[74:77], off sc1
	v_max_f32_e32 v69, 0, v69
	v_lshl_add_u64 v[82:83], v[156:157], 0, s[26:27]
	v_mul_f32_e32 v74, v66, v66
	v_max_f32_e32 v66, 0, v71
	v_mul_f32_e32 v71, v67, v67
	v_max_f32_e32 v67, 0, v72
	v_mul_f32_e32 v72, v68, v68
	v_max_f32_e32 v68, 0, v73
	v_mul_f32_e32 v67, v67, v67
	v_mul_f32_e32 v68, v68, v68
	v_max_f32_e32 v70, 0, v70
	v_mul_f32_e32 v66, v66, v66
	v_mul_f32_e32 v69, v69, v69
	v_cvt_pk_bf16_f32 v67, v67, v68
	v_cvt_pk_bf16_f32 v68, v74, v71
	v_mul_f32_e32 v70, v70, v70
	v_cvt_pk_bf16_f32 v66, v70, v66
	v_cvt_pk_bf16_f32 v69, v72, v69
	global_store_dwordx4 v[82:83], v[66:69], off offset:256 sc1
	s_mov_b32 s19, 0x120000
	s_mov_b64 s[26:27], 0x120000
	v_mov_b32_e32 v68, v87
	v_pk_mul_f32 v[58:59], v[58:59], v[68:69] op_sel_hi:[1,0]
	v_pk_mul_f32 v[62:63], v[62:63], v[68:69] op_sel_hi:[1,0]
	v_pk_mul_f32 v[60:61], v[60:61], v[68:69] op_sel_hi:[1,0]
	v_max_f32_e32 v58, 0, v58
	v_pk_mul_f32 v[64:65], v[64:65], v[68:69] op_sel_hi:[1,0]
	v_max_f32_e32 v62, 0, v62
	v_mul_f32_e32 v69, v58, v58
	v_max_f32_e32 v58, 0, v63
	v_max_f32_e32 v59, 0, v59
	v_max_f32_e32 v60, 0, v60
	v_mul_f32_e32 v62, v62, v62
	v_mul_f32_e32 v58, v58, v58
	v_mul_f32_e32 v63, v59, v59
	v_max_f32_e32 v59, 0, v64
	v_mul_f32_e32 v64, v60, v60
	v_max_f32_e32 v60, 0, v65
	v_mul_f32_e32 v59, v59, v59
	v_max_f32_e32 v61, 0, v61
	v_mul_f32_e32 v60, v60, v60
	v_cvt_pk_bf16_f32 v58, v62, v58
	v_add_co_u32_e32 v62, vcc, s19, v156
	v_pk_mul_f32 v[50:51], v[50:51], v[68:69] op_sel_hi:[1,0]
	v_mul_f32_e32 v61, v61, v61
	v_cvt_pk_bf16_f32 v59, v59, v60
	v_cvt_pk_bf16_f32 v60, v69, v63
	v_addc_co_u32_e32 v63, vcc, 0, v157, vcc
	v_pk_mul_f32 v[54:55], v[54:55], v[68:69] op_sel_hi:[1,0]
	v_max_f32_e32 v50, 0, v50
	v_cvt_pk_bf16_f32 v61, v64, v61
	global_store_dwordx4 v[62:63], v[58:61], off sc1
	v_max_f32_e32 v54, 0, v54
	v_mul_f32_e32 v54, v54, v54
	v_mul_f32_e32 v58, v50, v50
	v_max_f32_e32 v50, 0, v55
	v_mul_f32_e32 v50, v50, v50
	v_cvt_pk_bf16_f32 v50, v54, v50
	ds_read2_b32 v[54:55], v165 offset0:160 offset1:176
	v_pk_mul_f32 v[52:53], v[52:53], v[68:69] op_sel_hi:[1,0]
	v_pk_mul_f32 v[56:57], v[56:57], v[68:69] op_sel_hi:[1,0]
	v_max_f32_e32 v51, 0, v51
	v_max_f32_e32 v52, 0, v52
	v_mul_f32_e32 v59, v51, v51
	v_max_f32_e32 v51, 0, v56
	v_mul_f32_e32 v56, v52, v52
	v_max_f32_e32 v52, 0, v57
	v_mul_f32_e32 v51, v51, v51
	v_max_f32_e32 v53, 0, v53
	v_mul_f32_e32 v52, v52, v52
	s_waitcnt lgkmcnt(0)
	v_pk_mul_f32 v[42:43], v[42:43], v[54:55] op_sel_hi:[1,0]
	v_lshl_add_u64 v[66:67], v[156:157], 0, s[26:27]
	v_mul_f32_e32 v53, v53, v53
	v_cvt_pk_bf16_f32 v51, v51, v52
	v_cvt_pk_bf16_f32 v52, v58, v59
	v_pk_mul_f32 v[46:47], v[46:47], v[54:55] op_sel_hi:[1,0]
	v_pk_mul_f32 v[44:45], v[44:45], v[54:55] op_sel_hi:[1,0]
	v_max_f32_e32 v42, 0, v42
	v_cvt_pk_bf16_f32 v53, v56, v53
	global_store_dwordx4 v[66:67], v[50:53], off offset:256 sc1
	v_pk_mul_f32 v[48:49], v[48:49], v[54:55] op_sel_hi:[1,0]
	v_max_f32_e32 v46, 0, v46
	v_mul_f32_e32 v52, v42, v42
	v_max_f32_e32 v42, 0, v47
	v_max_f32_e32 v43, 0, v43
	v_max_f32_e32 v44, 0, v44
	v_mul_f32_e32 v46, v46, v46
	v_mul_f32_e32 v42, v42, v42
	v_mul_f32_e32 v47, v43, v43
	v_max_f32_e32 v43, 0, v48
	v_mul_f32_e32 v48, v44, v44
	v_max_f32_e32 v44, 0, v49
	s_mov_b32 s19, 0x140000
	v_mul_f32_e32 v43, v43, v43
	v_max_f32_e32 v45, 0, v45
	v_mul_f32_e32 v44, v44, v44
	v_cvt_pk_bf16_f32 v42, v46, v42
	v_add_co_u32_e32 v46, vcc, s19, v156
	v_pk_mul_f32 v[36:37], v[36:37], v[54:55] op_sel_hi:[1,0]
	v_pk_mul_f32 v[34:35], v[34:35], v[54:55] op_sel_hi:[1,0]
	v_mul_f32_e32 v45, v45, v45
	v_cvt_pk_bf16_f32 v43, v43, v44
	v_cvt_pk_bf16_f32 v44, v52, v47
	v_addc_co_u32_e32 v47, vcc, 0, v157, vcc
	v_pk_mul_f32 v[40:41], v[40:41], v[54:55] op_sel_hi:[1,0]
	v_pk_mul_f32 v[38:39], v[38:39], v[54:55] op_sel_hi:[1,0]
	v_max_f32_e32 v34, 0, v34
	v_max_f32_e32 v35, 0, v35
	v_max_f32_e32 v36, 0, v36
	v_cvt_pk_bf16_f32 v45, v48, v45
	global_store_dwordx4 v[46:47], v[42:45], off sc1
	s_mov_b64 s[26:27], 0x140000
	v_max_f32_e32 v37, 0, v37
	v_mul_f32_e32 v42, v34, v34
	v_max_f32_e32 v34, 0, v39
	v_mul_f32_e32 v39, v35, v35
	v_max_f32_e32 v35, 0, v40
	v_mul_f32_e32 v40, v36, v36
	v_max_f32_e32 v36, 0, v41
	v_mul_f32_e32 v35, v35, v35
	v_mul_f32_e32 v36, v36, v36
	v_lshl_add_u64 v[50:51], v[156:157], 0, s[26:27]
	v_max_f32_e32 v38, 0, v38
	v_mul_f32_e32 v34, v34, v34
	v_mul_f32_e32 v37, v37, v37
	v_cvt_pk_bf16_f32 v35, v35, v36
	v_cvt_pk_bf16_f32 v36, v42, v39
	v_mul_f32_e32 v38, v38, v38
	v_cvt_pk_bf16_f32 v34, v38, v34
	v_cvt_pk_bf16_f32 v37, v40, v37
	global_store_dwordx4 v[50:51], v[34:37], off offset:256 sc1
	s_mov_b32 s19, 0x160000
	s_mov_b64 s[26:27], 0x160000
	v_mov_b32_e32 v36, v55
	v_pk_mul_f32 v[26:27], v[26:27], v[36:37] op_sel_hi:[1,0]
	v_pk_mul_f32 v[30:31], v[30:31], v[36:37] op_sel_hi:[1,0]
	v_pk_mul_f32 v[28:29], v[28:29], v[36:37] op_sel_hi:[1,0]
	v_max_f32_e32 v26, 0, v26
	v_pk_mul_f32 v[32:33], v[32:33], v[36:37] op_sel_hi:[1,0]
	v_max_f32_e32 v30, 0, v30
	v_mul_f32_e32 v37, v26, v26
	v_max_f32_e32 v26, 0, v31
	v_max_f32_e32 v27, 0, v27
	v_max_f32_e32 v28, 0, v28
	v_mul_f32_e32 v30, v30, v30
	v_mul_f32_e32 v26, v26, v26
	v_mul_f32_e32 v31, v27, v27
	v_max_f32_e32 v27, 0, v32
	v_mul_f32_e32 v32, v28, v28
	v_max_f32_e32 v28, 0, v33
	v_mul_f32_e32 v27, v27, v27
	v_max_f32_e32 v29, 0, v29
	v_mul_f32_e32 v28, v28, v28
	v_cvt_pk_bf16_f32 v26, v30, v26
	v_add_co_u32_e32 v30, vcc, s19, v156
	v_pk_mul_f32 v[20:21], v[20:21], v[36:37] op_sel_hi:[1,0]
	v_pk_mul_f32 v[18:19], v[18:19], v[36:37] op_sel_hi:[1,0]
	v_mul_f32_e32 v29, v29, v29
	v_cvt_pk_bf16_f32 v27, v27, v28
	v_cvt_pk_bf16_f32 v28, v37, v31
	v_addc_co_u32_e32 v31, vcc, 0, v157, vcc
	v_pk_mul_f32 v[24:25], v[24:25], v[36:37] op_sel_hi:[1,0]
	v_pk_mul_f32 v[22:23], v[22:23], v[36:37] op_sel_hi:[1,0]
	v_max_f32_e32 v18, 0, v18
	v_max_f32_e32 v19, 0, v19
	v_max_f32_e32 v20, 0, v20
	v_cvt_pk_bf16_f32 v29, v32, v29
	global_store_dwordx4 v[30:31], v[26:29], off sc1
	v_max_f32_e32 v21, 0, v21
	v_lshl_add_u64 v[34:35], v[156:157], 0, s[26:27]
	v_mul_f32_e32 v26, v18, v18
	v_max_f32_e32 v18, 0, v23
	v_mul_f32_e32 v23, v19, v19
	v_max_f32_e32 v19, 0, v24
	v_mul_f32_e32 v24, v20, v20
	v_max_f32_e32 v20, 0, v25
	v_max_f32_e32 v22, 0, v22
	v_mul_f32_e32 v18, v18, v18
	v_mul_f32_e32 v19, v19, v19
	v_mul_f32_e32 v20, v20, v20
	v_mul_f32_e32 v21, v21, v21
	v_mul_f32_e32 v22, v22, v22
	v_cvt_pk_bf16_f32 v18, v22, v18
	v_cvt_pk_bf16_f32 v19, v19, v20
	v_cvt_pk_bf16_f32 v20, v26, v23
	v_cvt_pk_bf16_f32 v21, v24, v21
	global_store_dwordx4 v[34:35], v[18:21], off offset:256 sc1
	s_and_saveexec_b64 s[26:27], s[28:29]
	s_cbranch_execz .LBB0_1230
	s_waitcnt vmcnt(16)
	v_mov_b32_e32 v18, v3
	v_mov_b32_e32 v19, v4
	v_mov_b32_e32 v20, v2
	v_mov_b32_e32 v21, v5
	v_pk_add_f32 v[18:19], v[18:19], v[20:21]
	v_mov_b32_e32 v20, v7
	v_mov_b32_e32 v21, v8
	v_mov_b32_e32 v22, v6
	v_mov_b32_e32 v23, v9
	v_pk_add_f32 v[20:21], v[20:21], v[22:23]
	v_pk_add_f32 v[18:19], v[18:19], v[18:19] op_sel:[0,1] op_sel_hi:[1,0]
	v_pk_add_f32 v[20:21], v[20:21], v[20:21] op_sel:[0,1] op_sel_hi:[1,0]
	v_add_f32_e32 v22, v10, v11
	v_add_f32_e32 v24, v12, v13
	v_mov_b32_e32 v19, v14
	v_mov_b32_e32 v21, v15
	v_mov_b32_e32 v23, v16
	v_mov_b32_e32 v25, v17
	v_pk_add_f32 v[18:19], v[18:19], v[20:21]
	v_pk_add_f32 v[20:21], v[22:23], v[24:25]
	s_lshl_b32 s19, s65, 10
	v_pk_add_f32 v[18:19], v[18:19], v[20:21]
	s_xor_b32 s19, s19, 0x400
	v_add_f32_e32 v18, v18, v19
	v_fmamk_f32 v18, v18, 0x3a800000, v234
	v_mul_f32_e32 v19, 0x4b800000, v18
	v_cmp_gt_f32_e32 vcc, s33, v18
	s_nop 1
	v_cndmask_b32_e32 v18, v18, v19, vcc
	v_rsq_f32_e32 v18, v18
	s_nop 0
	v_mul_f32_e32 v19, 0x45800000, v18
	v_cndmask_b32_e32 v18, v18, v19, vcc
	v_add_u32_e32 v19, s19, v163
	ds_write_b32 v19, v18
